# team-locality check (XCC id table) hoisted from the P1|P2 seam into the P0|P1 seam under its buffer_inv wait, result parked in v240 lane 42; on p4pipe
# baseline (speedup 1.0000x reference)
; __global__ void __launch_bounds__(NWAVES * 64, 2) fwd(Args args) {
;     ...
;         if (whole && tid == 0) {
;             bool same = true;
;             for (int j = 0; j < 4; ++j) same = same && (__hip_atomic_load((unsigned*)(ctl + CW_XCCT) + (bx & 63) + 64 * j, RLX_AGENT) == bar.x + 1u);
;             if (!same) __hip_atomic_store((unsigned*)(ctl + CW_NONLOCAL), 1u, RLX_AGENT);
;         }
.Lts0_done:
	buffer_inv sc1
	s_and_b32 s3, s2, 63
	s_lshl_b32 s3, s3, 2
	s_add_u32 s8, s60, s3
	s_addc_u32 s9, s61, 0
	v_mov_b32_e32 v1, 0x28000
	global_load_dword v2, v1, s[8:9] sc1
	global_load_dword v3, v1, s[8:9] offset:256 sc1
	global_load_dword v4, v1, s[8:9] offset:512 sc1
	global_load_dword v5, v1, s[8:9] offset:768 sc1
	s_waitcnt vmcnt(0)
	v_xor_b32_e32 v3, v2, v3
	v_xor_b32_e32 v4, v2, v4
	v_xor_b32_e32 v5, v2, v5
	v_or3_b32 v2, v3, v4, v5
	s_nop 0
	v_readfirstlane_b32 s3, v2
	s_nop 3
	v_writelane_b32 v240, s3, 42

; __device__ __forceinline__ unsigned xb_ld(unsigned* p)              { return __hip_atomic_load(p, __ATOMIC_RELAXED, __HIP_MEMORY_SCOPE_AGENT); }
; __device__ __forceinline__ unsigned xb_add(unsigned* p, unsigned v) { return __hip_atomic_fetch_add(p, v, __ATOMIC_RELAXED, __HIP_MEMORY_SCOPE_AGENT); }
; #define XB_SPIN(cond, bar) do { unsigned _sp = 0; while (cond) { __builtin_amdgcn_s_sleep(1); \
;     if ((++_sp & 255u) == 0u) { if (xb_ld(&(bar)[XB_TMO])) break; if (_sp > XB_SPIN_CAP) { atomicAdd(&(bar)[XB_TMO], 1u); break; } } } } while (0)
; __device__ __forceinline__ void team_barrier(unsigned* ctr, unsigned target, unsigned* bar) {
;     asm volatile("s_waitcnt vmcnt(0)" ::: "memory");
;     __syncthreads();
;     if (threadIdx.x == 0) {
;         __builtin_amdgcn_s_waitcnt(0);
;         (void)xb_add(ctr, 1u);
;         asm volatile("buffer_inv sc1" ::: "memory");
;         XB_SPIN(xb_ld(ctr) < target, bar);
;         asm volatile("s_waitcnt vmcnt(0)" ::: "memory");
;     }
;     __syncthreads();
; }
; __global__ void __launch_bounds__(NWAVES * 64, 2) fwd(Args args) {
;     ...
;         if (whole && tid == 0) {
;             bool same = true;
;             for (int j = 0; j < 4; ++j) same = same && (__hip_atomic_load((unsigned*)(ctl + CW_XCCT) + (bx & 63) + 64 * j, RLX_AGENT) == bar.x + 1u);
;             if (!same) __hip_atomic_store((unsigned*)(ctl + CW_NONLOCAL), 1u, RLX_AGENT);
.Lts1_a:
	s_or_b64 exec, exec, s[6:7]
	s_waitcnt vmcnt(0)
	s_barrier
	s_and_saveexec_b64 s[6:7], s[96:97]
	s_cbranch_execz .Lts1_join
	v_readlane_b32 s3, v240, 42
	s_nop 1
	s_cmp_eq_u32 s3, 0
	s_cbranch_scc1 .Lts1_nowb
	buffer_wbl2 sc1
	s_waitcnt vmcnt(0)
